# grid barrier: non-leader workgroups poll the cross-XCD release word directly instead of the per-XCD relay word
# speedup vs baseline: 1.0099x; 1.0099x over previous
.LBB0_590:
	v_readlane_b32 s4, v251, 10
	v_readlane_b32 s5, v251, 11
	v_cvt_f32_u32_e32 v1, v3
	v_sub_u32_e32 v5, 0, v3
	v_rcp_iflag_f32_e32 v1, v1
	s_nop 1
	global_atomic_add v4, v131, v220, s[4:5] sc0
	v_mul_f32_e32 v1, 0x4f7ffffe, v1
	v_cvt_u32_f32_e32 v1, v1
	v_mul_lo_u32 v5, v5, v1
	v_mul_hi_u32 v5, v1, v5
	v_add_u32_e32 v1, v1, v5
	s_waitcnt vmcnt(0)
	v_mul_hi_u32 v1, v4, v1
	v_mul_lo_u32 v5, v1, v3
	v_sub_u32_e32 v5, v4, v5
	v_add_u32_e32 v6, 1, v1
	v_cmp_ge_u32_e32 vcc, v5, v3
	v_add_u32_e32 v4, 1, v4
	s_nop 0
	v_cndmask_b32_e32 v1, v1, v6, vcc
	v_sub_u32_e32 v6, v5, v3
	v_cndmask_b32_e32 v5, v5, v6, vcc
	v_add_u32_e32 v6, 1, v1
	v_cmp_ge_u32_e32 vcc, v5, v3
	s_nop 1
	v_cndmask_b32_e32 v1, v1, v6, vcc
	v_mul_lo_u32 v5, v3, v1
	v_add_u32_e32 v3, v5, v3
	v_cmp_ne_u32_e32 vcc, v4, v3
	s_and_saveexec_b64 s[4:5], vcc
	s_xor_b64 s[28:29], exec, s[4:5]
	s_cbranch_execz .LBB0_604
	v_readlane_b32 s4, v251, 16
	v_readlane_b32 s5, v251, 17
	s_waitcnt lgkmcnt(0)
	s_nop 3
	global_load_dword v2, v131, s[4:5] sc1
	s_waitcnt vmcnt(0)
	v_cmp_eq_u32_e32 vcc, v2, v1
	s_and_saveexec_b64 s[30:31], vcc
	s_cbranch_execz .LBB0_603
	s_mov_b32 s4, 1
	s_mov_b64 s[36:37], 0
	s_branch .LBB0_594
